# banded mode-2: next tile's V loads issued at the end of the tile (one address reg, offsets -4096..3072), first V tile in the item prologue (on top of v50)
# baseline (speedup 1.0000x reference)
.LBB0_895:
	s_or_b64 exec, exec, s[0:1]
	s_and_b64 vcc, exec, s[10:11]
	s_waitcnt lgkmcnt(0)
	s_barrier
	s_cbranch_vccz .LBB0_910
	v_readlane_b32 s0, v255, 29
	s_cmp_lg_u32 s0, 1
	s_mov_b64 s[0:1], -1
	s_mov_b32 s8, 0xc2fc0000
	s_cbranch_scc0 .LBB0_912
	s_mov_b64 s[42:43], s[76:77]
	s_mov_b64 s[38:39], s[76:77]
	s_mov_b64 s[40:41], s[76:77]
	s_mov_b64 s[0:1], s[76:77]
	s_mov_b64 s[4:5], s[76:77]
	v_mov_b32_e32 v0, v239
	v_readlane_b32 s4, v254, 24
	v_readlane_b32 s5, v254, 25
	s_andn2_b64 vcc, exec, s[4:5]
	s_cbranch_vccnz .LBB0_911
	v_ashrrev_i32_e32 v1, 5, v0
	v_lshlrev_b32_e32 v2, 3, v1
	v_ashrrev_i32_e32 v3, 31, v2
	v_lshl_add_u64 v[2:3], v[2:3], 1, s[42:43]
	s_mov_b64 s[4:5], 0xa000000
	v_lshl_add_u64 v[180:181], v[2:3], 0, s[4:5]
	v_lshlrev_b32_e32 v2, 4, v0
	v_ashrrev_i32_e32 v3, 31, v2
	v_lshlrev_b32_e32 v202, 2, v1
	v_and_b32_e32 v1, 64, v238
	v_and_b32_e32 v178, 31, v0
	v_lshl_add_u64 v[4:5], s[38:39], 0, v[2:3]
	s_mov_b64 s[4:5], 0xe800000
	v_cmp_gt_u32_e32 vcc, 32, v0
	v_xor_b32_e32 v0, 32, v238
	v_add_u32_e32 v1, 64, v1
	v_lshl_add_u64 v[182:183], v[4:5], 0, s[4:5]
	v_lshl_add_u64 v[2:3], s[40:41], 0, v[2:3]
	s_mov_b64 s[4:5], 0x10001000
	v_cndmask_b32_e64 v179, 0, 1.0, vcc
	v_cmp_lt_i32_e32 vcc, v0, v1
	s_add_u32 s0, s0, 0x11800000
	v_lshl_add_u64 v[184:185], v[2:3], 0, s[4:5]
	v_cndmask_b32_e32 v0, v238, v0, vcc
	v_readlane_b32 s4, v253, 20
	s_addc_u32 s1, s1, 0
	v_lshlrev_b32_e32 v210, 2, v0
	v_ashrrev_i32_e32 v203, 31, v202
	v_sub_u32_e32 v211, v202, v178
	v_readlane_b32 s46, v254, 32
	s_mov_b32 s47, s4
	v_readlane_b32 s5, v253, 21
	s_branch .LBB0_901

.LBB0_901:
	s_lshl_b32 s4, s47, 5
	s_and_b32 s50, s4, 0xfe0
	s_add_i32 s5, s50, 0x9f
	s_add_i32 s4, s50, 0xffffff80
	s_lshr_b32 s5, s5, 6
	s_bfe_u32 s48, s47, 0x40007
	s_ashr_i32 s49, s47, 11
	s_ashr_i32 s4, s4, 6
	s_add_i32 s5, s5, 1
	s_cmpk_lt_u32 s50, 0xf61
	s_cselect_b32 s51, s5, 64
	v_mov_b32_e32 v49, 0
	s_cmp_ge_i32 s4, s51
	v_mov_b32_e32 v48, 0
	v_mov_b32_e32 v47, 0
	v_mov_b32_e32 v46, 0
	v_mov_b32_e32 v45, 0
	v_mov_b32_e32 v44, 0
	v_mov_b32_e32 v43, 0
	v_mov_b32_e32 v42, 0
	v_mov_b32_e32 v41, 0
	v_mov_b32_e32 v40, 0
	v_mov_b32_e32 v39, 0
	v_mov_b32_e32 v38, 0
	v_mov_b32_e32 v37, 0
	v_mov_b32_e32 v36, 0
	v_mov_b32_e32 v35, 0
	v_mov_b32_e32 v34, 0
	v_mov_b32_e32 v65, 0
	v_mov_b32_e32 v64, 0
	v_mov_b32_e32 v63, 0
	v_mov_b32_e32 v62, 0
	v_mov_b32_e32 v61, 0
	v_mov_b32_e32 v60, 0
	v_mov_b32_e32 v59, 0
	v_mov_b32_e32 v58, 0
	v_mov_b32_e32 v57, 0
	v_mov_b32_e32 v56, 0
	v_mov_b32_e32 v55, 0
	v_mov_b32_e32 v54, 0
	v_mov_b32_e32 v53, 0
	v_mov_b32_e32 v52, 0
	v_mov_b32_e32 v51, 0
	v_mov_b32_e32 v50, 0
	v_mov_b32_e32 v214, v179
	s_cbranch_scc1 .LBB0_900
	s_and_b32 s5, s46, 0xfe0
	v_subrev_u32_e32 v212, s5, v211
	s_lshl_b32 s5, s49, 4
	s_or_b32 s6, s5, s48
	s_ashr_i32 s7, s6, 31
	s_lshl_b64 s[6:7], s[6:7], 12
	s_or_b32 s5, s6, s50
	v_mov_b32_e32 v1, s7
	v_or_b32_e32 v0, s5, v178
	s_lshr_b32 s5, s48, 2
	s_lshl_b32 s6, s49, 2
	v_lshlrev_b64 v[0:1], 7, v[0:1]
	s_or_b32 s6, s5, s6
	s_not_b32 s5, s48
	v_lshl_add_u64 v[0:1], v[180:181], 0, v[0:1]
	s_lshl_b32 s5, s5, 3
	global_load_dwordx4 v[98:101], v[0:1], off
	global_load_dwordx4 v[102:105], v[0:1], off offset:32
	global_load_dwordx4 v[106:109], v[0:1], off offset:64
	global_load_dwordx4 v[110:113], v[0:1], off offset:96
	v_cvt_f32_i32_e32 v0, s5
	s_ashr_i32 s7, s6, 31
	s_lshl_b64 s[6:7], s[6:7], 19
	v_lshl_add_u64 v[204:205], v[182:183], 0, s[6:7]
	v_mul_f32_e32 v1, 0x3d800000, v0
	v_cmp_gt_f32_e32 vcc, s8, v1
	v_lshl_add_u64 v[206:207], v[184:185], 0, s[6:7]
	s_and_b64 s[6:7], vcc, exec
	v_cndmask_b32_e32 v1, 0, v241, vcc
	v_fmac_f32_e32 v1, 0x3d800000, v0
	v_exp_f32_e32 v0, v1
	s_cselect_b32 s5, 0xffffffc0, 0
	s_mov_b64 s[6:7], s[58:59]
	s_mov_b32 s8, s65
	v_ldexp_f32 v0, v0, s5
	s_lshl_b32 s5, s48, 2
	v_mul_f32_e32 v4, 0x3fb8aa3b, v0
	v_mov_b32_e32 v0, s5
	s_mov_b32 s5, s64
	s_mov_b32 s9, s57
	v_readlane_b32 s52, v253, 2
	v_readlane_b32 s56, v253, 6
	v_readlane_b32 s57, v253, 7
	s_max_i32 s52, s4, 0
	s_lshl_b32 s16, s52, 13
	v_mov_b32_e32 v46, v33
	v_mov_b32_e32 v47, v33
	v_mov_b32_e32 v32, v33
	global_load_dword v0, v0, s[56:57]
	v_lshl_add_u64 v[6:7], v[204:205], 0, s[16:17]
	v_add_co_u32_e32 v8, vcc, s79, v6
	v_mov_b32_e32 v34, v33
	v_mov_b32_e32 v35, v33
	v_addc_co_u32_e32 v9, vcc, 0, v7, vcc
	global_load_dwordx4 v[114:117], v[8:9], off offset:3072
	global_load_dwordx4 v[118:121], v[8:9], off offset:2048
	global_load_dwordx4 v[122:125], v[8:9], off offset:1024
	global_load_dwordx4 v[126:129], v[8:9], off
	global_load_dwordx4 v[130:133], v[6:7], off offset:3072
	global_load_dwordx4 v[134:137], v[6:7], off offset:2048
	global_load_dwordx4 v[138:141], v[6:7], off offset:1024
	global_load_dwordx4 v[142:145], v[6:7], off
	v_lshl_add_u64 v[10:11], v[206:207], 0, s[16:17]
	global_load_dwordx4 v[174:177], v[10:11], off offset:-4096
	global_load_dwordx4 v[170:173], v[10:11], off offset:-3072
	global_load_dwordx4 v[166:169], v[10:11], off offset:-2048
	global_load_dwordx4 v[162:165], v[10:11], off offset:-1024
	global_load_dwordx4 v[158:161], v[10:11], off
	global_load_dwordx4 v[154:157], v[10:11], off offset:1024
	global_load_dwordx4 v[150:153], v[10:11], off offset:2048
	global_load_dwordx4 v[146:149], v[10:11], off offset:3072
	v_mov_b32_e32 v36, v33
	v_mov_b32_e32 v37, v33
	v_mov_b32_e32 v38, v33
	v_mov_b32_e32 v39, v33
	v_mov_b32_e32 v40, v33
	v_mov_b32_e32 v41, v33
	v_mov_b32_e32 v42, v33
	v_mov_b32_e32 v43, v33
	v_mov_b32_e32 v44, v33
	v_mov_b32_e32 v45, v33
	v_mov_b64_e32 v[64:65], v[46:47]
	v_readlane_b32 s53, v253, 3
	v_readlane_b32 s54, v253, 4
	v_readlane_b32 s55, v253, 5
	v_readlane_b32 s58, v253, 8
	v_readlane_b32 s59, v253, 9
	v_readlane_b32 s60, v253, 10
	v_readlane_b32 s61, v253, 11
	v_readlane_b32 s62, v253, 12
	v_readlane_b32 s63, v253, 13
	v_readlane_b32 s64, v253, 14
	v_readlane_b32 s65, v253, 15
	v_readlane_b32 s66, v253, 16
	v_readlane_b32 s67, v253, 17
	v_readfirstlane_b32 s38, v4
	v_mov_b64_e32 v[62:63], v[44:45]
	v_mov_b64_e32 v[60:61], v[42:43]
	v_mov_b64_e32 v[58:59], v[40:41]
	v_mov_b64_e32 v[56:57], v[38:39]
	v_mov_b64_e32 v[54:55], v[36:37]
	v_mov_b64_e32 v[52:53], v[34:35]
	v_mov_b64_e32 v[50:51], v[32:33]
	v_mov_b64_e32 v[48:49], v[46:47]
	s_mov_b32 s65, s8
	s_mov_b32 s64, s5
	s_mov_b64 s[58:59], s[6:7]
	s_mov_b32 s57, s9
	s_add_i32 s53, s50, 0x42
	s_add_i32 s54, s50, 0xffffff9e
	s_mov_b32 s39, s38
	s_mov_b32 s55, s38
	s_mov_b32 s60, s38
	s_mov_b32 s61, s38
	s_mov_b32 s62, s38
	s_mov_b32 s63, s38
	s_mov_b32 s66, s38
	s_mov_b32 s67, s38
	s_mov_b32 s69, s38
	s_mov_b32 s70, s38
	s_mov_b32 s71, s38
	s_mov_b32 s80, s38
	s_mov_b32 s81, s38
	s_mov_b32 s82, s38
	s_mov_b32 s83, s38
	s_mov_b32 s84, s38
	s_mov_b32 s85, s38
	s_mov_b32 s86, s38
	s_mov_b32 s87, s38
	s_mov_b32 s88, s38
	s_mov_b32 s89, s38
	s_mov_b32 s93, s38
	s_mov_b32 s94, s38
	s_mov_b32 s95, s38
	s_mov_b32 s96, s38
	s_mov_b32 s97, s38
	s_mov_b32 s4, s38
	s_mov_b32 s5, s38
	s_mov_b32 s6, s38
	s_mov_b32 s7, s38
	s_mov_b32 s8, s38
	s_lshl_b32 s9, s52, 6
	s_mov_b64 s[40:41], s[16:17]
	v_mov_b64_e32 v[46:47], v[44:45]
	v_mov_b64_e32 v[44:45], v[42:43]
	v_mov_b64_e32 v[42:43], v[40:41]
	v_mov_b64_e32 v[40:41], v[38:39]
	v_mov_b64_e32 v[38:39], v[36:37]
	s_waitcnt vmcnt(16)
	v_mul_f32_e32 v213, 0x3fb8aa3b, v0
	v_mov_b64_e32 v[36:37], v[34:35]
	v_mov_b64_e32 v[34:35], v[32:33]
	v_mov_b32_e32 v214, v179
	s_branch .LBB0_904
.LBB0_903:
	v_sub_f32_e32 v0, v0, v213
	v_exp_f32_e32 v0, v0
	v_sub_f32_e32 v1, v1, v213
	v_exp_f32_e32 v1, v1
	v_sub_f32_e32 v2, v2, v213
	v_exp_f32_e32 v2, v2
	v_sub_f32_e32 v3, v3, v213
	v_exp_f32_e32 v3, v3
	v_sub_f32_e32 v4, v4, v213
	v_add_f32_e32 v32, 0, v0
	v_exp_f32_e32 v4, v4
	v_sub_f32_e32 v5, v5, v213
	v_add_f32_e32 v32, v1, v32
	v_exp_f32_e32 v5, v5
	v_sub_f32_e32 v6, v6, v213
	v_add_f32_e32 v32, v2, v32
	v_exp_f32_e32 v6, v6
	v_sub_f32_e32 v7, v7, v213
	v_add_f32_e32 v32, v3, v32
	v_exp_f32_e32 v7, v7
	v_sub_f32_e32 v8, v8, v213
	v_add_f32_e32 v32, v4, v32
	v_exp_f32_e32 v66, v8
	v_add_f32_e32 v32, v5, v32
	v_add_f32_e32 v32, v6, v32
	v_add_f32_e32 v32, v7, v32
	v_sub_f32_e32 v9, v9, v213
	v_add_f32_e32 v8, v66, v32
	v_exp_f32_e32 v32, v9
	v_sub_f32_e32 v9, v10, v213
	v_exp_f32_e32 v67, v9
	v_sub_f32_e32 v9, v11, v213
	v_exp_f32_e32 v68, v9
	v_sub_f32_e32 v9, v12, v213
	v_exp_f32_e32 v69, v9
	v_sub_f32_e32 v9, v13, v213
	v_add_f32_e32 v8, v32, v8
	v_exp_f32_e32 v70, v9
	v_sub_f32_e32 v9, v14, v213
	v_add_f32_e32 v8, v67, v8
	v_exp_f32_e32 v71, v9
	v_sub_f32_e32 v9, v15, v213
	v_add_f32_e32 v8, v68, v8
	v_exp_f32_e32 v15, v9
	v_sub_f32_e32 v9, v16, v213
	v_add_f32_e32 v8, v69, v8
	v_exp_f32_e32 v16, v9
	v_sub_f32_e32 v9, v17, v213
	v_add_f32_e32 v8, v70, v8
	v_exp_f32_e32 v17, v9
	v_sub_f32_e32 v9, v18, v213
	v_add_f32_e32 v8, v71, v8
	v_exp_f32_e32 v18, v9
	v_sub_f32_e32 v9, v19, v213
	v_add_f32_e32 v8, v15, v8
	v_exp_f32_e32 v19, v9
	v_sub_f32_e32 v9, v20, v213
	v_add_f32_e32 v8, v16, v8
	v_exp_f32_e32 v20, v9
	v_sub_f32_e32 v9, v21, v213
	v_add_f32_e32 v8, v17, v8
	v_exp_f32_e32 v21, v9
	v_sub_f32_e32 v9, v22, v213
	v_add_f32_e32 v8, v18, v8
	v_exp_f32_e32 v22, v9
	v_sub_f32_e32 v9, v23, v213
	v_add_f32_e32 v8, v19, v8
	v_exp_f32_e32 v23, v9
	v_sub_f32_e32 v9, v24, v213
	v_add_f32_e32 v8, v20, v8
	v_exp_f32_e32 v24, v9
	v_sub_f32_e32 v9, v25, v213
	v_add_f32_e32 v8, v21, v8
	v_exp_f32_e32 v25, v9
	v_sub_f32_e32 v9, v26, v213
	v_add_f32_e32 v8, v22, v8
	v_exp_f32_e32 v26, v9
	v_sub_f32_e32 v9, v27, v213
	v_add_f32_e32 v8, v23, v8
	v_exp_f32_e32 v27, v9
	v_sub_f32_e32 v9, v28, v213
	v_add_f32_e32 v8, v24, v8
	v_exp_f32_e32 v28, v9
	v_sub_f32_e32 v9, v29, v213
	v_add_f32_e32 v8, v25, v8
	v_exp_f32_e32 v29, v9
	v_sub_f32_e32 v9, v30, v213
	v_add_f32_e32 v8, v26, v8
	v_exp_f32_e32 v30, v9
	v_sub_f32_e32 v9, v31, v213
	v_add_f32_e32 v8, v27, v8
	v_exp_f32_e32 v31, v9
	v_add_f32_e32 v8, v28, v8
	v_add_f32_e32 v8, v29, v8
	v_add_f32_e32 v8, v30, v8
	v_add_f32_e32 v72, v31, v8
	v_cvt_pk_bf16_f32 v8, v0, v1
	v_cvt_pk_bf16_f32 v9, v2, v3
	v_cvt_pk_bf16_f32 v10, v4, v5
	v_cvt_pk_bf16_f32 v11, v6, v7
	v_cvt_pk_bf16_f32 v12, v66, v32
	v_cvt_pk_bf16_f32 v13, v67, v68
	s_waitcnt vmcnt(15)
	v_mfma_f32_32x32x16_bf16 v[50:65], v[174:177], v[8:11], v[50:65]
	v_cvt_pk_bf16_f32 v14, v69, v70
	v_cvt_pk_bf16_f32 v15, v71, v15
	v_cvt_pk_bf16_f32 v4, v16, v17
	v_cvt_pk_bf16_f32 v5, v18, v19
	v_cvt_pk_bf16_f32 v6, v20, v21
	v_cvt_pk_bf16_f32 v7, v22, v23
	v_cvt_pk_bf16_f32 v0, v24, v25
	s_waitcnt vmcnt(11)
	v_mfma_f32_32x32x16_bf16 v[34:49], v[158:161], v[8:11], v[34:49]
	v_cvt_pk_bf16_f32 v1, v26, v27
	v_cvt_pk_bf16_f32 v2, v28, v29
	v_cvt_pk_bf16_f32 v3, v30, v31
	v_add_f32_e32 v214, v214, v72
	s_add_i32 s9, s9, 64
	s_and_b64 vcc, exec, s[42:43]
	v_mfma_f32_32x32x16_bf16 v[50:65], v[170:173], v[12:15], v[50:65]
	s_waitcnt vmcnt(10)
	v_mfma_f32_32x32x16_bf16 v[34:49], v[154:157], v[12:15], v[34:49]
	v_mfma_f32_32x32x16_bf16 v[50:65], v[166:169], v[4:7], v[50:65]
	s_waitcnt vmcnt(9)
	v_mfma_f32_32x32x16_bf16 v[34:49], v[150:153], v[4:7], v[34:49]
	v_mfma_f32_32x32x16_bf16 v[50:65], v[162:165], v[0:3], v[50:65]
	s_waitcnt vmcnt(8)
	v_mfma_f32_32x32x16_bf16 v[34:49], v[146:149], v[0:3], v[34:49]
	v_lshl_add_u64 v[16:17], v[206:207], 0, s[40:41]
	global_load_dwordx4 v[174:177], v[16:17], off offset:-4096
	global_load_dwordx4 v[170:173], v[16:17], off offset:-3072
	global_load_dwordx4 v[166:169], v[16:17], off offset:-2048
	global_load_dwordx4 v[162:165], v[16:17], off offset:-1024
	global_load_dwordx4 v[158:161], v[16:17], off
	global_load_dwordx4 v[154:157], v[16:17], off offset:1024
	global_load_dwordx4 v[150:153], v[16:17], off offset:2048
	global_load_dwordx4 v[146:149], v[16:17], off offset:3072
	s_cbranch_vccnz .LBB0_899
.LBB0_904:
	s_waitcnt vmcnt(8)
	v_mfma_f32_32x32x16_bf16 v[66:81], v[142:145], v[98:101], 0
	s_mov_b32 s10, s52
	s_add_i32 s52, s52, 1
	s_cmp_ge_u32 s52, s51
	s_cselect_b64 s[42:43], -1, 0
	s_cmp_lt_u32 s52, s51
	v_mfma_f32_32x32x16_bf16 v[82:97], v[126:129], v[98:101], 0
	s_cselect_b32 s16, s52, s10
	s_lshl_b64 s[40:41], s[16:17], 13
	v_mfma_f32_32x32x16_bf16 v[66:81], v[138:141], v[102:105], v[66:81]
	v_lshl_add_u64 v[0:1], v[204:205], 0, s[40:41]
	global_load_dwordx4 v[142:145], v[0:1], off
	global_load_dwordx4 v[138:141], v[0:1], off offset:1024
	s_cmp_lt_u32 s9, s53
	s_cselect_b64 s[10:11], -1, 0
	s_cmp_gt_i32 s9, s54
	s_cselect_b64 s[44:45], -1, 0
	s_and_b64 s[10:11], s[10:11], s[44:45]
	v_mfma_f32_32x32x16_bf16 v[82:97], v[122:125], v[102:105], v[82:97]
	s_mov_b64 s[44:45], -1
	v_mfma_f32_32x32x16_bf16 v[66:81], v[134:137], v[106:109], v[66:81]
	v_mfma_f32_32x32x16_bf16 v[82:97], v[118:121], v[106:109], v[82:97]
	v_mfma_f32_32x32x16_bf16 v[66:81], v[130:133], v[110:113], v[66:81]
	global_load_dwordx4 v[134:137], v[0:1], off offset:2048
	global_load_dwordx4 v[130:133], v[0:1], off offset:3072
	v_add_co_u32_e32 v0, vcc, s79, v0
	s_nop 1
	v_addc_co_u32_e32 v1, vcc, 0, v1, vcc
	global_load_dwordx4 v[126:129], v[0:1], off
	global_load_dwordx4 v[122:125], v[0:1], off offset:1024
	v_mfma_f32_32x32x16_bf16 v[82:97], v[114:117], v[110:113], v[82:97]
	global_load_dwordx4 v[118:121], v[0:1], off offset:2048
	global_load_dwordx4 v[114:117], v[0:1], off offset:3072
	v_add_u32_e32 v0, s9, v212
	v_cvt_f32_i32_e32 v32, v0
	s_and_b64 vcc, exec, s[10:11]
	v_add_f32_e32 v215, 1.0, v32
	v_and_b32_e32 v208, 0x7fffffff, v32
	v_and_b32_e32 v209, 0x7fffffff, v215
	s_cbranch_vccnz .LBB0_906
	v_add_f32_e32 v1, 1.0, v32
	v_cmp_le_f32_e64 vcc, |v32|, s92
	v_cmp_le_f32_e64 s[10:11], |v1|, s92
	v_fma_f32 v0, s38, -|v32|, v66
	v_fma_f32 v1, s38, -|v1|, v67
	v_cndmask_b32_e32 v0, v242, v0, vcc
	v_cndmask_b32_e64 v1, v242, v1, s[10:11]
	v_add_f32_e32 v2, 2.0, v32
	v_add_f32_e32 v3, 0x40400000, v32
	v_cmp_le_f32_e64 vcc, |v2|, s92
	v_cmp_le_f32_e64 s[10:11], |v3|, s92
	v_fma_f32 v2, s38, -|v2|, v68
	v_fma_f32 v3, s38, -|v3|, v69
	v_cndmask_b32_e32 v2, v242, v2, vcc
	v_cndmask_b32_e64 v3, v242, v3, s[10:11]
	v_add_f32_e32 v4, 0x41000000, v32
	v_add_f32_e32 v5, 0x41100000, v32
	v_cmp_le_f32_e64 vcc, |v4|, s92
	v_cmp_le_f32_e64 s[10:11], |v5|, s92
	v_fma_f32 v4, s38, -|v4|, v70
	v_fma_f32 v5, s38, -|v5|, v71
	v_cndmask_b32_e32 v4, v242, v4, vcc
	v_cndmask_b32_e64 v5, v242, v5, s[10:11]
	v_add_f32_e32 v6, 0x41200000, v32
	v_add_f32_e32 v7, 0x41300000, v32
	v_cmp_le_f32_e64 vcc, |v6|, s92
	v_cmp_le_f32_e64 s[10:11], |v7|, s92
	v_fma_f32 v6, s38, -|v6|, v72
	v_fma_f32 v7, s38, -|v7|, v73
	v_cndmask_b32_e32 v6, v242, v6, vcc
	v_cndmask_b32_e64 v7, v242, v7, s[10:11]
	v_add_f32_e32 v8, 0x41800000, v32
	v_add_f32_e32 v9, 0x41880000, v32
	v_cmp_le_f32_e64 vcc, |v8|, s92
	v_cmp_le_f32_e64 s[10:11], |v9|, s92
	v_fma_f32 v8, s38, -|v8|, v74
	v_fma_f32 v9, s38, -|v9|, v75
	v_cndmask_b32_e32 v8, v242, v8, vcc
	v_cndmask_b32_e64 v9, v242, v9, s[10:11]
	v_add_f32_e32 v10, 0x41900000, v32
	v_add_f32_e32 v11, 0x41980000, v32
	v_cmp_le_f32_e64 vcc, |v10|, s92
	v_cmp_le_f32_e64 s[10:11], |v11|, s92
	v_fma_f32 v10, s38, -|v10|, v76
	v_fma_f32 v11, s38, -|v11|, v77
	v_cndmask_b32_e32 v10, v242, v10, vcc
	v_cndmask_b32_e64 v11, v242, v11, s[10:11]
	v_add_f32_e32 v12, 0x41c00000, v32
	v_add_f32_e32 v13, 0x41c80000, v32
	v_cmp_le_f32_e64 vcc, |v12|, s92
	v_cmp_le_f32_e64 s[10:11], |v13|, s92
	v_fma_f32 v12, s38, -|v12|, v78
	v_fma_f32 v13, s38, -|v13|, v79
	v_cndmask_b32_e32 v12, v242, v12, vcc
	v_cndmask_b32_e64 v13, v242, v13, s[10:11]
	v_add_f32_e32 v14, 0x41d00000, v32
	v_add_f32_e32 v15, 0x41d80000, v32
	v_cmp_le_f32_e64 vcc, |v14|, s92
	v_cmp_le_f32_e64 s[10:11], |v15|, s92
	v_fma_f32 v14, s38, -|v14|, v80
	v_fma_f32 v15, s38, -|v15|, v81
	v_cndmask_b32_e32 v14, v242, v14, vcc
	v_cndmask_b32_e64 v15, v242, v15, s[10:11]
	v_add_f32_e32 v16, 0x42000000, v32
	v_add_f32_e32 v17, 0x42040000, v32
	v_cmp_le_f32_e64 vcc, |v16|, s92
	v_cmp_le_f32_e64 s[10:11], |v17|, s92
	v_fma_f32 v16, s38, -|v16|, v82
	v_fma_f32 v17, s38, -|v17|, v83
	v_cndmask_b32_e32 v16, v242, v16, vcc
	v_cndmask_b32_e64 v17, v242, v17, s[10:11]
	v_add_f32_e32 v18, 0x42080000, v32
	v_add_f32_e32 v19, 0x420c0000, v32
	v_cmp_le_f32_e64 vcc, |v18|, s92
	v_cmp_le_f32_e64 s[10:11], |v19|, s92
	v_fma_f32 v18, s38, -|v18|, v84
	v_fma_f32 v19, s38, -|v19|, v85
	v_cndmask_b32_e32 v18, v242, v18, vcc
	v_cndmask_b32_e64 v19, v242, v19, s[10:11]
	v_add_f32_e32 v20, 0x42200000, v32
	v_add_f32_e32 v21, 0x42240000, v32
	v_cmp_le_f32_e64 vcc, |v20|, s92
	v_cmp_le_f32_e64 s[10:11], |v21|, s92
	v_fma_f32 v20, s38, -|v20|, v86
	v_fma_f32 v21, s38, -|v21|, v87
	v_cndmask_b32_e32 v20, v242, v20, vcc
	v_cndmask_b32_e64 v21, v242, v21, s[10:11]
	v_add_f32_e32 v22, 0x42280000, v32
	v_add_f32_e32 v23, 0x422c0000, v32
	v_cmp_le_f32_e64 vcc, |v22|, s92
	v_cmp_le_f32_e64 s[10:11], |v23|, s92
	v_fma_f32 v22, s38, -|v22|, v88
	v_fma_f32 v23, s38, -|v23|, v89
	v_cndmask_b32_e32 v22, v242, v22, vcc
	v_cndmask_b32_e64 v23, v242, v23, s[10:11]
	v_add_f32_e32 v24, 0x42400000, v32
	v_add_f32_e32 v25, 0x42440000, v32
	v_cmp_le_f32_e64 vcc, |v24|, s92
	v_cmp_le_f32_e64 s[10:11], |v25|, s92
	v_fma_f32 v24, s38, -|v24|, v90
	v_fma_f32 v25, s38, -|v25|, v91
	v_cndmask_b32_e32 v24, v242, v24, vcc
	v_cndmask_b32_e64 v25, v242, v25, s[10:11]
	v_add_f32_e32 v26, 0x42480000, v32
	v_add_f32_e32 v27, 0x424c0000, v32
	v_cmp_le_f32_e64 vcc, |v26|, s92
	v_cmp_le_f32_e64 s[10:11], |v27|, s92
	v_fma_f32 v26, s38, -|v26|, v92
	v_fma_f32 v27, s38, -|v27|, v93
	v_cndmask_b32_e32 v26, v242, v26, vcc
	v_cndmask_b32_e64 v27, v242, v27, s[10:11]
	v_add_f32_e32 v28, 0x42600000, v32
	v_add_f32_e32 v29, 0x42640000, v32
	v_cmp_le_f32_e64 vcc, |v28|, s92
	v_cmp_le_f32_e64 s[10:11], |v29|, s92
	v_fma_f32 v28, s38, -|v28|, v94
	v_fma_f32 v29, s38, -|v29|, v95
	v_cndmask_b32_e32 v28, v242, v28, vcc
	v_cndmask_b32_e64 v29, v242, v29, s[10:11]
	v_add_f32_e32 v30, 0x42680000, v32
	v_add_f32_e32 v31, 0x426c0000, v32
	v_cmp_le_f32_e64 vcc, |v30|, s92
	v_cmp_le_f32_e64 s[10:11], |v31|, s92
	v_fma_f32 v30, s38, -|v30|, v96
	v_fma_f32 v31, s38, -|v31|, v97
	v_cndmask_b32_e32 v30, v242, v30, vcc
	v_cndmask_b32_e64 v31, v242, v31, s[10:11]
	s_mov_b64 s[44:45], 0
